# v18 + nt on once-read epilogue loads (gates in branch GEMMs, h1 residual in ffn-down)
# baseline (speedup 1.0000x reference)
; __device__ __forceinline__ unsigned pk_bf16(float lo, float hi) { const f32x2 v = {lo, hi}; return __builtin_bit_cast(unsigned, __builtin_convertvector(v, b16x2)); }
;     __device__ __forceinline__ void row(int r, int col32, int fq, const f32x4& a00, const f32x4& a01, const f32x4& a10, const f32x4& a11) const { half(r, col32, fq, a00, a01); half(r, col32 + HALF, fq, a10, a11); }
;     __device__ __forceinline__ void row(int r, int col32, int fq, const f32x4& a00, const f32x4& a01, const f32x4& a10, const f32x4& a11) const { half(r, col32, fq, a00, a01); half(r, col32 + HALF, fq, a10, a11); }
;     ...
;             const int brow = cur.pm * BM, bcol = cur.pn * BM;
; #pragma unroll
;             for (int ai = 0; ai < 2; ++ai)
; #pragma unroll
;                 for (int m = 0; m < 4; ++m) {
;                     E.row(brow + ai * HALF + wr * 64 + m * 16 + fr, bcol + wc * 32, fq, acc[ai][0][m][0], acc[ai][0][m][1], acc[ai][1][m][0], acc[ai][1][m][1]);
;                     asm volatile("" ::: "memory");
;                 }
;     __device__ __forceinline__ void half(int row, int col32, int fq, const f32x4& v0, const f32x4& v1) const {
;         const int col = col32 + 8 * fq;
;         float g[8]; bf8_to_f(*(const u32x4*)(gates + (size_t)row * 2048 + col), g);
;         u32x4 w; w.x = pk_bf16(v0[0] * g[0], v0[1] * g[1]); w.y = pk_bf16(v0[2] * g[2], v0[3] * g[3]); w.z = pk_bf16(v1[0] * g[4], v1[1] * g[5]); w.w = pk_bf16(v1[2] * g[6], v1[3] * g[7]);
;         *(u32x4*)(t1 + (size_t)row * D + col) = w;
;     }
;     __device__ __forceinline__ void row(int r, int col32, int fq, const f32x4& a00, const f32x4& a01, const f32x4& a10, const f32x4& a11) const { half(r, col32, fq, a00, a01); half(r, col32 + HALF, fq, a10, a11); }
.LBB0_1026:
	v_lshl_add_u32 v154, s24, 8, v129
	v_lshl_or_b32 v152, s46, 8, v135
	v_ashrrev_i32_e32 v155, 31, v154
	v_ashrrev_i32_e32 v153, 31, v152
	v_lshlrev_b64 v[176:177], 12, v[154:155]
	v_lshl_add_u64 v[176:177], s[88:89], 0, v[176:177]
	v_lshlrev_b64 v[152:153], 1, v[152:153]
	v_add_u32_e32 v184, 0x0, v154
	v_ashrrev_i32_e32 v185, 31, v184
	v_lshlrev_b64 v[186:187], 12, v[184:185]
	v_lshl_add_u64 v[186:187], s[88:89], 0, v[186:187]
	v_lshl_add_u64 v[186:187], v[186:187], 0, v[152:153]
	global_load_dwordx4 v[188:191], v[186:187], off nt
	global_load_dwordx4 v[192:195], v[186:187], off offset:256 nt
	s_nop 0
	v_add_u32_e32 v184, 0x10, v154
	v_ashrrev_i32_e32 v185, 31, v184
	v_lshlrev_b64 v[186:187], 12, v[184:185]
	v_lshl_add_u64 v[186:187], s[88:89], 0, v[186:187]
	v_lshl_add_u64 v[186:187], v[186:187], 0, v[152:153]
	global_load_dwordx4 v[196:199], v[186:187], off nt
	global_load_dwordx4 v[200:203], v[186:187], off offset:256 nt
	s_nop 0
	v_add_u32_e32 v184, 0x20, v154
	v_ashrrev_i32_e32 v185, 31, v184
	v_lshlrev_b64 v[186:187], 12, v[184:185]
	v_lshl_add_u64 v[186:187], s[88:89], 0, v[186:187]
	v_lshl_add_u64 v[186:187], v[186:187], 0, v[152:153]
	global_load_dwordx4 v[204:207], v[186:187], off nt
	global_load_dwordx4 v[208:211], v[186:187], off offset:256 nt
	s_nop 0
	v_add_u32_e32 v184, 0x30, v154
	v_ashrrev_i32_e32 v185, 31, v184
	v_lshlrev_b64 v[186:187], 12, v[184:185]
	v_lshl_add_u64 v[186:187], s[88:89], 0, v[186:187]
	v_lshl_add_u64 v[186:187], v[186:187], 0, v[152:153]
	global_load_dwordx4 v[212:215], v[186:187], off nt
	global_load_dwordx4 v[216:219], v[186:187], off offset:256 nt
	s_nop 0
	v_add_u32_e32 v184, 0x80, v154
	v_ashrrev_i32_e32 v185, 31, v184
	v_lshlrev_b64 v[186:187], 12, v[184:185]
	v_lshl_add_u64 v[186:187], s[88:89], 0, v[186:187]
	v_lshl_add_u64 v[186:187], v[186:187], 0, v[152:153]
	global_load_dwordx4 v[220:223], v[186:187], off nt
	global_load_dwordx4 v[228:231], v[186:187], off offset:256 nt
	s_nop 0
	v_add_u32_e32 v184, 0x90, v154
	v_ashrrev_i32_e32 v185, 31, v184
	v_lshlrev_b64 v[186:187], 12, v[184:185]
	v_lshl_add_u64 v[186:187], s[88:89], 0, v[186:187]
	v_lshl_add_u64 v[186:187], v[186:187], 0, v[152:153]
	global_load_dwordx4 v[232:235], v[186:187], off nt
	global_load_dwordx4 v[236:239], v[186:187], off offset:256 nt
	s_nop 0
	v_add_u32_e32 v184, 0xa0, v154
	v_ashrrev_i32_e32 v185, 31, v184
	v_lshlrev_b64 v[186:187], 12, v[184:185]
	v_lshl_add_u64 v[186:187], s[88:89], 0, v[186:187]
	v_lshl_add_u64 v[186:187], v[186:187], 0, v[152:153]
	global_load_dwordx4 v[240:243], v[186:187], off nt
	global_load_dwordx4 v[244:247], v[186:187], off offset:256 nt
	s_nop 0
	v_lshl_add_u64 v[180:181], v[176:177], 0, v[152:153]
	v_lshlrev_b64 v[182:183], 11, v[154:155]
	v_lshl_add_u64 v[182:183], s[8:9], 0, v[182:183]
	v_lshl_add_u64 v[182:183], v[182:183], 0, v[152:153]
	s_andn2_b64 vcc, exec, s[4:5]
	s_mov_b64 s[4:5], -1
	s_waitcnt vmcnt(0)
	v_lshlrev_b32_e32 v184, 16, v188
	v_and_b32_e32 v185, 0xffff0000, v188
	v_lshlrev_b32_e32 v176, 16, v189
	v_and_b32_e32 v177, 0xffff0000, v189
	v_lshlrev_b32_e32 v186, 16, v190
	v_and_b32_e32 v187, 0xffff0000, v190
	v_lshlrev_b32_e32 v178, 16, v191
	v_and_b32_e32 v179, 0xffff0000, v191
	v_pk_mul_f32 v[124:125], v[124:125], v[184:185]
	v_pk_mul_f32 v[126:127], v[126:127], v[176:177]
	v_pk_mul_f32 v[176:177], v[120:121], v[186:187]
	v_pk_mul_f32 v[178:179], v[122:123], v[178:179]
	v_cvt_pk_bf16_f32 v120, v124, v125
	v_cvt_pk_bf16_f32 v121, v126, v127
	v_cvt_pk_bf16_f32 v122, v176, v177
	v_cvt_pk_bf16_f32 v123, v178, v179
	global_store_dwordx4 v[182:183], v[120:123], off
	v_or_b32_e32 v124, 16, v154
	v_ashrrev_i32_e32 v125, 31, v124
	v_lshlrev_b64 v[126:127], 12, v[124:125]
	v_lshl_add_u64 v[126:127], s[88:89], 0, v[126:127]
	v_lshl_add_u64 v[126:127], v[126:127], 0, v[152:153]
	v_lshlrev_b32_e32 v176, 16, v192
	v_and_b32_e32 v177, 0xffff0000, v192
	v_lshlrev_b32_e32 v120, 16, v193
	v_and_b32_e32 v121, 0xffff0000, v193
	v_lshlrev_b32_e32 v178, 16, v194
	v_and_b32_e32 v179, 0xffff0000, v194
	v_lshlrev_b32_e32 v122, 16, v195
	v_and_b32_e32 v123, 0xffff0000, v195
	v_add_u32_e32 v184, 0xb0, v154
	v_ashrrev_i32_e32 v185, 31, v184
	v_lshlrev_b64 v[186:187], 12, v[184:185]
	v_lshl_add_u64 v[186:187], s[88:89], 0, v[186:187]
	v_lshl_add_u64 v[186:187], v[186:187], 0, v[152:153]
	global_load_dwordx4 v[188:191], v[186:187], off nt
	global_load_dwordx4 v[192:195], v[186:187], off offset:256 nt
	s_nop 0
	v_pk_mul_f32 v[116:117], v[116:117], v[176:177]
	v_pk_mul_f32 v[118:119], v[118:119], v[120:121]
	v_pk_mul_f32 v[120:121], v[112:113], v[178:179]
	v_pk_mul_f32 v[122:123], v[114:115], v[122:123]
	v_cvt_pk_bf16_f32 v112, v116, v117
	v_cvt_pk_bf16_f32 v113, v118, v119
	v_cvt_pk_bf16_f32 v114, v120, v121
	v_cvt_pk_bf16_f32 v115, v122, v123
	global_store_dwordx4 v[182:183], v[112:115], off offset:256
	v_lshlrev_b64 v[116:117], 11, v[124:125]
	v_lshl_add_u64 v[116:117], s[8:9], 0, v[116:117]
	v_lshl_add_u64 v[116:117], v[116:117], 0, v[152:153]
	v_lshlrev_b32_e32 v118, 16, v196
	v_and_b32_e32 v119, 0xffff0000, v196
	v_lshlrev_b32_e32 v112, 16, v197
	v_and_b32_e32 v113, 0xffff0000, v197
	v_lshlrev_b32_e32 v120, 16, v198
	v_and_b32_e32 v121, 0xffff0000, v198
	v_lshlrev_b32_e32 v114, 16, v199
	v_and_b32_e32 v115, 0xffff0000, v199
	v_pk_mul_f32 v[108:109], v[108:109], v[118:119]
	v_pk_mul_f32 v[110:111], v[110:111], v[112:113]
	v_pk_mul_f32 v[112:113], v[104:105], v[120:121]
	v_pk_mul_f32 v[114:115], v[106:107], v[114:115]
	v_cvt_pk_bf16_f32 v104, v108, v109
	v_cvt_pk_bf16_f32 v105, v110, v111
	v_cvt_pk_bf16_f32 v106, v112, v113
	v_cvt_pk_bf16_f32 v107, v114, v115
	global_store_dwordx4 v[116:117], v[104:107], off
; __device__ __forceinline__ unsigned pk_bf16(float lo, float hi) { const f32x2 v = {lo, hi}; return __builtin_bit_cast(unsigned, __builtin_convertvector(v, b16x2)); }
;     __device__ __forceinline__ void row(int r, int col32, int fq, const f32x4& a00, const f32x4& a01, const f32x4& a10, const f32x4& a11) const { half(r, col32, fq, a00, a01); half(r, col32 + HALF, fq, a10, a11); }
;     __device__ __forceinline__ void row(int r, int col32, int fq, const f32x4& a00, const f32x4& a01, const f32x4& a10, const f32x4& a11) const { half(r, col32, fq, a00, a01); half(r, col32 + HALF, fq, a10, a11); }
;     __device__ __forceinline__ void row(int r, int col32, int fq, const f32x4& a00, const f32x4& a01, const f32x4& a10, const f32x4& a11) const { half(r, col32, fq, a00, a01); half(r, col32 + HALF, fq, a10, a11); }
;     __device__ __forceinline__ void half(int row, int col32, int fq, const f32x4& v0, const f32x4& v1) const {
;         const int col = col32 + 8 * fq;
;         float g[8]; bf8_to_f(*(const u32x4*)(gates + (size_t)row * 2048 + col), g);
;         u32x4 w; w.x = pk_bf16(v0[0] * g[0], v0[1] * g[1]); w.y = pk_bf16(v0[2] * g[2], v0[3] * g[3]); w.z = pk_bf16(v1[0] * g[4], v1[1] * g[5]); w.w = pk_bf16(v1[2] * g[6], v1[3] * g[7]);
;         *(u32x4*)(t1 + (size_t)row * D + col) = w;
	v_or_b32_e32 v108, 32, v154
	v_ashrrev_i32_e32 v109, 31, v108
	v_lshlrev_b64 v[110:111], 12, v[108:109]
	v_lshl_add_u64 v[110:111], s[88:89], 0, v[110:111]
	v_lshl_add_u64 v[110:111], v[110:111], 0, v[152:153]
	v_lshlrev_b32_e32 v112, 16, v200
	v_and_b32_e32 v113, 0xffff0000, v200
	v_lshlrev_b32_e32 v104, 16, v201
	v_and_b32_e32 v105, 0xffff0000, v201
	v_lshlrev_b32_e32 v114, 16, v202
	v_and_b32_e32 v115, 0xffff0000, v202
	v_lshlrev_b32_e32 v106, 16, v203
	v_and_b32_e32 v107, 0xffff0000, v203
	v_pk_mul_f32 v[100:101], v[100:101], v[112:113]
	v_pk_mul_f32 v[102:103], v[102:103], v[104:105]
	v_pk_mul_f32 v[104:105], v[96:97], v[114:115]
	v_pk_mul_f32 v[106:107], v[98:99], v[106:107]
	v_cvt_pk_bf16_f32 v96, v100, v101
	v_cvt_pk_bf16_f32 v97, v102, v103
	v_cvt_pk_bf16_f32 v98, v104, v105
	v_cvt_pk_bf16_f32 v99, v106, v107
	global_store_dwordx4 v[116:117], v[96:99], off offset:256
	v_lshlrev_b64 v[100:101], 11, v[108:109]
	v_lshl_add_u64 v[100:101], s[8:9], 0, v[100:101]
	v_lshl_add_u64 v[100:101], v[100:101], 0, v[152:153]
	v_lshlrev_b32_e32 v102, 16, v204
	v_and_b32_e32 v103, 0xffff0000, v204
	v_lshlrev_b32_e32 v96, 16, v205
	v_and_b32_e32 v97, 0xffff0000, v205
	v_lshlrev_b32_e32 v104, 16, v206
	v_and_b32_e32 v105, 0xffff0000, v206
	v_lshlrev_b32_e32 v98, 16, v207
	v_and_b32_e32 v99, 0xffff0000, v207
	v_pk_mul_f32 v[92:93], v[92:93], v[102:103]
	v_pk_mul_f32 v[94:95], v[94:95], v[96:97]
	v_pk_mul_f32 v[96:97], v[88:89], v[104:105]
	v_pk_mul_f32 v[98:99], v[90:91], v[98:99]
	v_cvt_pk_bf16_f32 v88, v92, v93
	v_cvt_pk_bf16_f32 v89, v94, v95
	v_cvt_pk_bf16_f32 v90, v96, v97
	v_cvt_pk_bf16_f32 v91, v98, v99
	global_store_dwordx4 v[100:101], v[88:91], off
	v_or_b32_e32 v92, 48, v154
	v_ashrrev_i32_e32 v93, 31, v92
	v_lshlrev_b64 v[94:95], 12, v[92:93]
	v_lshl_add_u64 v[94:95], s[88:89], 0, v[94:95]
	v_lshl_add_u64 v[94:95], v[94:95], 0, v[152:153]
	v_lshlrev_b32_e32 v96, 16, v208
	v_and_b32_e32 v97, 0xffff0000, v208
	v_lshlrev_b32_e32 v88, 16, v209
	v_and_b32_e32 v89, 0xffff0000, v209
	v_lshlrev_b32_e32 v98, 16, v210
	v_and_b32_e32 v99, 0xffff0000, v210
	v_lshlrev_b32_e32 v90, 16, v211
	v_and_b32_e32 v91, 0xffff0000, v211
	v_pk_mul_f32 v[84:85], v[84:85], v[96:97]
	v_pk_mul_f32 v[86:87], v[86:87], v[88:89]
	v_pk_mul_f32 v[88:89], v[80:81], v[98:99]
	v_pk_mul_f32 v[90:91], v[82:83], v[90:91]
	v_cvt_pk_bf16_f32 v80, v84, v85
	v_cvt_pk_bf16_f32 v81, v86, v87
	v_cvt_pk_bf16_f32 v82, v88, v89
	v_cvt_pk_bf16_f32 v83, v90, v91
	global_store_dwordx4 v[100:101], v[80:83], off offset:256
	v_lshlrev_b64 v[84:85], 11, v[92:93]
	v_lshl_add_u64 v[84:85], s[8:9], 0, v[84:85]
	v_lshl_add_u64 v[84:85], v[84:85], 0, v[152:153]
	v_lshlrev_b32_e32 v86, 16, v212
	v_and_b32_e32 v87, 0xffff0000, v212
	v_lshlrev_b32_e32 v80, 16, v213
	v_and_b32_e32 v81, 0xffff0000, v213
	v_lshlrev_b32_e32 v88, 16, v214
	v_and_b32_e32 v89, 0xffff0000, v214
	v_lshlrev_b32_e32 v82, 16, v215
	v_and_b32_e32 v83, 0xffff0000, v215
	v_pk_mul_f32 v[76:77], v[76:77], v[86:87]
	v_pk_mul_f32 v[78:79], v[78:79], v[80:81]
	v_pk_mul_f32 v[80:81], v[72:73], v[88:89]
	v_pk_mul_f32 v[82:83], v[74:75], v[82:83]
	v_cvt_pk_bf16_f32 v72, v76, v77
	v_cvt_pk_bf16_f32 v73, v78, v79
	v_cvt_pk_bf16_f32 v74, v80, v81
	v_cvt_pk_bf16_f32 v75, v82, v83
	global_store_dwordx4 v[84:85], v[72:75], off
	v_add_u32_e32 v76, 0x80, v154
	v_ashrrev_i32_e32 v77, 31, v76
	v_lshlrev_b64 v[78:79], 12, v[76:77]
	v_lshl_add_u64 v[78:79], s[88:89], 0, v[78:79]
	v_lshl_add_u64 v[78:79], v[78:79], 0, v[152:153]
	v_lshlrev_b32_e32 v80, 16, v216
	v_and_b32_e32 v81, 0xffff0000, v216
	v_lshlrev_b32_e32 v72, 16, v217
	v_and_b32_e32 v73, 0xffff0000, v217
	v_lshlrev_b32_e32 v82, 16, v218
	v_and_b32_e32 v83, 0xffff0000, v218
	v_lshlrev_b32_e32 v74, 16, v219
	v_and_b32_e32 v75, 0xffff0000, v219
	v_pk_mul_f32 v[68:69], v[68:69], v[80:81]
	v_pk_mul_f32 v[70:71], v[70:71], v[72:73]
	v_pk_mul_f32 v[72:73], v[64:65], v[82:83]
	v_pk_mul_f32 v[74:75], v[66:67], v[74:75]
	v_cvt_pk_bf16_f32 v64, v68, v69
	v_cvt_pk_bf16_f32 v65, v70, v71
	v_cvt_pk_bf16_f32 v66, v72, v73
	v_cvt_pk_bf16_f32 v67, v74, v75
	global_store_dwordx4 v[84:85], v[64:67], off offset:256
	v_lshlrev_b64 v[68:69], 11, v[76:77]
	v_lshl_add_u64 v[68:69], s[8:9], 0, v[68:69]
	v_lshl_add_u64 v[68:69], v[68:69], 0, v[152:153]
	v_lshlrev_b32_e32 v70, 16, v220
	v_and_b32_e32 v71, 0xffff0000, v220
	v_lshlrev_b32_e32 v64, 16, v221
	v_and_b32_e32 v65, 0xffff0000, v221
	v_lshlrev_b32_e32 v72, 16, v222
	v_and_b32_e32 v73, 0xffff0000, v222
	v_lshlrev_b32_e32 v66, 16, v223
	v_and_b32_e32 v67, 0xffff0000, v223
	v_pk_mul_f32 v[60:61], v[60:61], v[70:71]
	v_pk_mul_f32 v[62:63], v[62:63], v[64:65]
	v_pk_mul_f32 v[64:65], v[56:57], v[72:73]
	v_pk_mul_f32 v[66:67], v[58:59], v[66:67]
	v_cvt_pk_bf16_f32 v56, v60, v61
	v_cvt_pk_bf16_f32 v57, v62, v63
	v_cvt_pk_bf16_f32 v58, v64, v65
	v_cvt_pk_bf16_f32 v59, v66, v67
	global_store_dwordx4 v[68:69], v[56:59], off
	v_add_u32_e32 v60, 0x90, v154
	v_ashrrev_i32_e32 v61, 31, v60
	v_lshlrev_b64 v[62:63], 12, v[60:61]
	v_lshl_add_u64 v[62:63], s[88:89], 0, v[62:63]
	v_lshl_add_u64 v[62:63], v[62:63], 0, v[152:153]
	v_lshlrev_b32_e32 v64, 16, v228
	v_and_b32_e32 v65, 0xffff0000, v228
	v_lshlrev_b32_e32 v56, 16, v229
	v_and_b32_e32 v57, 0xffff0000, v229
; __device__ __forceinline__ unsigned pk_bf16(float lo, float hi) { const f32x2 v = {lo, hi}; return __builtin_bit_cast(unsigned, __builtin_convertvector(v, b16x2)); }
; #define PG8_BAR __builtin_amdgcn_s_barrier()
;     __device__ __forceinline__ void row(int r, int col32, int fq, const f32x4& a00, const f32x4& a01, const f32x4& a10, const f32x4& a11) const { half(r, col32, fq, a00, a01); half(r, col32 + HALF, fq, a10, a11); }
;     __device__ __forceinline__ void row(int r, int col32, int fq, const f32x4& a00, const f32x4& a01, const f32x4& a10, const f32x4& a11) const { half(r, col32, fq, a00, a01); half(r, col32 + HALF, fq, a10, a11); }
;     ...
;         if (!has_next) break;
; #pragma unroll
;         for (int a = 0; a < 2; ++a)
; #pragma unroll
;             for (int b = 0; b < 2; ++b)
; #pragma unroll
;                 for (int m = 0; m < 4; ++m)
; #pragma unroll
;                     for (int n = 0; n < 2; ++n) acc[a][b][m][n] = (f32x4){0.f, 0.f, 0.f, 0.f};
;         cur = nxt; cA = nA; cB = nB; ++ui;
;         if (wr == 1) PG8_BAR;
;     __device__ __forceinline__ void half(int row, int col32, int fq, const f32x4& v0, const f32x4& v1) const {
;         const int col = col32 + 8 * fq;
;         float g[8]; bf8_to_f(*(const u32x4*)(gates + (size_t)row * 2048 + col), g);
;         u32x4 w; w.x = pk_bf16(v0[0] * g[0], v0[1] * g[1]); w.y = pk_bf16(v0[2] * g[2], v0[3] * g[3]); w.z = pk_bf16(v1[0] * g[4], v1[1] * g[5]); w.w = pk_bf16(v1[2] * g[6], v1[3] * g[7]);
;         *(u32x4*)(t1 + (size_t)row * D + col) = w;
;     }
;     __device__ __forceinline__ void row(int r, int col32, int fq, const f32x4& a00, const f32x4& a01, const f32x4& a10, const f32x4& a11) const { half(r, col32, fq, a00, a01); half(r, col32 + HALF, fq, a10, a11); }
	v_lshlrev_b32_e32 v66, 16, v230
	v_and_b32_e32 v67, 0xffff0000, v230
	v_lshlrev_b32_e32 v58, 16, v231
	v_and_b32_e32 v59, 0xffff0000, v231
	v_pk_mul_f32 v[52:53], v[52:53], v[64:65]
	v_pk_mul_f32 v[54:55], v[54:55], v[56:57]
	v_pk_mul_f32 v[56:57], v[48:49], v[66:67]
	v_pk_mul_f32 v[58:59], v[50:51], v[58:59]
	v_cvt_pk_bf16_f32 v48, v52, v53
	v_cvt_pk_bf16_f32 v49, v54, v55
	v_cvt_pk_bf16_f32 v50, v56, v57
	v_cvt_pk_bf16_f32 v51, v58, v59
	global_store_dwordx4 v[68:69], v[48:51], off offset:256
	v_lshlrev_b64 v[52:53], 11, v[60:61]
	v_lshl_add_u64 v[52:53], s[8:9], 0, v[52:53]
	v_lshl_add_u64 v[52:53], v[52:53], 0, v[152:153]
	v_lshlrev_b32_e32 v54, 16, v232
	v_and_b32_e32 v55, 0xffff0000, v232
	v_lshlrev_b32_e32 v48, 16, v233
	v_and_b32_e32 v49, 0xffff0000, v233
	v_lshlrev_b32_e32 v56, 16, v234
	v_and_b32_e32 v57, 0xffff0000, v234
	v_lshlrev_b32_e32 v50, 16, v235
	v_and_b32_e32 v51, 0xffff0000, v235
	v_pk_mul_f32 v[44:45], v[44:45], v[54:55]
	v_pk_mul_f32 v[46:47], v[46:47], v[48:49]
	v_pk_mul_f32 v[48:49], v[40:41], v[56:57]
	v_pk_mul_f32 v[50:51], v[42:43], v[50:51]
	v_cvt_pk_bf16_f32 v40, v44, v45
	v_cvt_pk_bf16_f32 v41, v46, v47
	v_cvt_pk_bf16_f32 v42, v48, v49
	v_cvt_pk_bf16_f32 v43, v50, v51
	global_store_dwordx4 v[52:53], v[40:43], off
	v_add_u32_e32 v44, 0xa0, v154
	v_ashrrev_i32_e32 v45, 31, v44
	v_lshlrev_b64 v[46:47], 12, v[44:45]
	v_lshl_add_u64 v[46:47], s[88:89], 0, v[46:47]
	v_lshl_add_u64 v[46:47], v[46:47], 0, v[152:153]
	v_lshlrev_b32_e32 v48, 16, v236
	v_and_b32_e32 v49, 0xffff0000, v236
	v_lshlrev_b32_e32 v40, 16, v237
	v_and_b32_e32 v41, 0xffff0000, v237
	v_lshlrev_b32_e32 v50, 16, v238
	v_and_b32_e32 v51, 0xffff0000, v238
	v_lshlrev_b32_e32 v42, 16, v239
	v_and_b32_e32 v43, 0xffff0000, v239
	v_pk_mul_f32 v[36:37], v[36:37], v[48:49]
	v_pk_mul_f32 v[38:39], v[38:39], v[40:41]
	v_pk_mul_f32 v[40:41], v[32:33], v[50:51]
	v_pk_mul_f32 v[42:43], v[34:35], v[42:43]
	v_cvt_pk_bf16_f32 v32, v36, v37
	v_cvt_pk_bf16_f32 v33, v38, v39
	v_cvt_pk_bf16_f32 v34, v40, v41
	v_cvt_pk_bf16_f32 v35, v42, v43
	global_store_dwordx4 v[52:53], v[32:35], off offset:256
	v_lshlrev_b64 v[36:37], 11, v[44:45]
	v_lshl_add_u64 v[36:37], s[8:9], 0, v[36:37]
	v_lshl_add_u64 v[36:37], v[36:37], 0, v[152:153]
	v_lshlrev_b32_e32 v38, 16, v240
	v_and_b32_e32 v39, 0xffff0000, v240
	v_lshlrev_b32_e32 v32, 16, v241
	v_and_b32_e32 v33, 0xffff0000, v241
	v_lshlrev_b32_e32 v40, 16, v242
	v_and_b32_e32 v41, 0xffff0000, v242
	v_lshlrev_b32_e32 v34, 16, v243
	v_and_b32_e32 v35, 0xffff0000, v243
	v_pk_mul_f32 v[28:29], v[28:29], v[38:39]
	v_pk_mul_f32 v[30:31], v[30:31], v[32:33]
	v_pk_mul_f32 v[32:33], v[24:25], v[40:41]
	v_pk_mul_f32 v[34:35], v[26:27], v[34:35]
	v_cvt_pk_bf16_f32 v24, v28, v29
	v_cvt_pk_bf16_f32 v25, v30, v31
	v_cvt_pk_bf16_f32 v26, v32, v33
	v_cvt_pk_bf16_f32 v27, v34, v35
	global_store_dwordx4 v[36:37], v[24:27], off
	v_add_u32_e32 v28, 0xb0, v154
	v_ashrrev_i32_e32 v29, 31, v28
	v_lshlrev_b64 v[30:31], 12, v[28:29]
	v_lshl_add_u64 v[30:31], s[88:89], 0, v[30:31]
	v_lshl_add_u64 v[30:31], v[30:31], 0, v[152:153]
	v_lshlrev_b32_e32 v32, 16, v244
	v_and_b32_e32 v33, 0xffff0000, v244
	v_lshlrev_b32_e32 v24, 16, v245
	v_and_b32_e32 v25, 0xffff0000, v245
	v_lshlrev_b32_e32 v34, 16, v246
	v_and_b32_e32 v35, 0xffff0000, v246
	v_lshlrev_b32_e32 v26, 16, v247
	v_and_b32_e32 v27, 0xffff0000, v247
	v_pk_mul_f32 v[20:21], v[20:21], v[32:33]
	v_pk_mul_f32 v[22:23], v[22:23], v[24:25]
	v_pk_mul_f32 v[24:25], v[16:17], v[34:35]
	v_pk_mul_f32 v[26:27], v[18:19], v[26:27]
	v_cvt_pk_bf16_f32 v16, v20, v21
	v_cvt_pk_bf16_f32 v17, v22, v23
	v_cvt_pk_bf16_f32 v18, v24, v25
	v_cvt_pk_bf16_f32 v19, v26, v27
	global_store_dwordx4 v[36:37], v[16:19], off offset:256
	v_lshlrev_b64 v[20:21], 11, v[28:29]
	v_lshl_add_u64 v[20:21], s[8:9], 0, v[20:21]
	v_lshl_add_u64 v[20:21], v[20:21], 0, v[152:153]
	s_waitcnt vmcnt(13)
	v_lshlrev_b32_e32 v22, 16, v188
	v_and_b32_e32 v23, 0xffff0000, v188
	v_lshlrev_b32_e32 v16, 16, v189
	v_and_b32_e32 v17, 0xffff0000, v189
	v_lshlrev_b32_e32 v24, 16, v190
	v_and_b32_e32 v25, 0xffff0000, v190
	v_lshlrev_b32_e32 v18, 16, v191
	v_and_b32_e32 v19, 0xffff0000, v191
	v_pk_mul_f32 v[12:13], v[12:13], v[22:23]
	v_pk_mul_f32 v[14:15], v[14:15], v[16:17]
	v_pk_mul_f32 v[16:17], v[8:9], v[24:25]
	v_pk_mul_f32 v[18:19], v[10:11], v[18:19]
	v_cvt_pk_bf16_f32 v8, v12, v13
	v_cvt_pk_bf16_f32 v9, v14, v15
	v_cvt_pk_bf16_f32 v10, v16, v17
	v_cvt_pk_bf16_f32 v11, v18, v19
	global_store_dwordx4 v[20:21], v[8:11], off
	v_lshlrev_b32_e32 v12, 16, v192
	v_and_b32_e32 v13, 0xffff0000, v192
	v_lshlrev_b32_e32 v8, 16, v193
	v_and_b32_e32 v9, 0xffff0000, v193
	v_lshlrev_b32_e32 v14, 16, v194
	v_and_b32_e32 v15, 0xffff0000, v194
	v_lshlrev_b32_e32 v10, 16, v195
	v_and_b32_e32 v11, 0xffff0000, v195
	v_pk_mul_f32 v[4:5], v[4:5], v[12:13]
	v_pk_mul_f32 v[6:7], v[6:7], v[8:9]
	v_pk_mul_f32 v[8:9], v[0:1], v[14:15]
	v_pk_mul_f32 v[10:11], v[2:3], v[10:11]
	v_cvt_pk_bf16_f32 v0, v4, v5
	v_cvt_pk_bf16_f32 v1, v6, v7
	v_cvt_pk_bf16_f32 v2, v8, v9
	v_cvt_pk_bf16_f32 v3, v10, v11
	global_store_dwordx4 v[20:21], v[0:3], off offset:256
	s_cbranch_vccnz .LBB0_1015
	s_andn2_b64 vcc, exec, s[6:7]
	s_cbranch_vccnz .LBB0_1014
	s_barrier
	s_branch .LBB0_1014

; __device__ __forceinline__ unsigned pk_bf16(float lo, float hi) { const f32x2 v = {lo, hi}; return __builtin_bit_cast(unsigned, __builtin_convertvector(v, b16x2)); }
;     __device__ __forceinline__ void row(int r, int col32, int fq, const f32x4& a00, const f32x4& a01, const f32x4& a10, const f32x4& a11) const { half(r, col32, fq, a00, a01); half(r, col32 + HALF, fq, a10, a11); }
;     __device__ __forceinline__ void row(int r, int col32, int fq, const f32x4& a00, const f32x4& a01, const f32x4& a10, const f32x4& a11) const { half(r, col32, fq, a00, a01); half(r, col32 + HALF, fq, a10, a11); }
;     __device__ __forceinline__ void half(int row, int col32, int fq, const f32x4& v0, const f32x4& v1) const {
;         const int col = col32 + 8 * fq;
;         float g[8], a[8]; bf8_to_f(*(const u32x4*)(gates + (size_t)row * 2048 + 1024 + col), g); bf8_to_f(*(const u32x4*)(t1 + (size_t)row * D + col), a);
;         u32x4 w; w.x = pk_bf16(a[0] + v0[0] * g[0], a[1] + v0[1] * g[1]); w.y = pk_bf16(a[2] + v0[2] * g[2], a[3] + v0[3] * g[3]);
;         w.z = pk_bf16(a[4] + v1[0] * g[4], a[5] + v1[1] * g[5]); w.w = pk_bf16(a[6] + v1[2] * g[6], a[7] + v1[3] * g[7]);
;         *(u32x4*)(m + (size_t)row * D + col) = w;
;     }
;     __device__ __forceinline__ void row(int r, int col32, int fq, const f32x4& a00, const f32x4& a01, const f32x4& a10, const f32x4& a11) const { half(r, col32, fq, a00, a01); half(r, col32 + HALF, fq, a10, a11); }
.LBB0_1050:
	v_lshl_add_u32 v154, s26, 8, v129
	v_lshl_or_b32 v152, s46, 8, v135
	v_ashrrev_i32_e32 v155, 31, v154
	v_ashrrev_i32_e32 v153, 31, v152
	v_lshlrev_b64 v[176:177], 12, v[154:155]
	v_lshlrev_b64 v[184:185], 11, v[154:155]
	v_lshl_add_u64 v[176:177], s[88:89], 0, v[176:177]
	v_lshlrev_b64 v[152:153], 1, v[152:153]
	v_add_u32_e32 v236, 0x0, v154
	v_ashrrev_i32_e32 v237, 31, v236
	v_lshlrev_b64 v[238:239], 12, v[236:237]
	v_lshlrev_b64 v[240:241], 11, v[236:237]
	v_lshl_add_u64 v[238:239], s[88:89], 0, v[238:239]
	v_lshl_add_u64 v[240:241], s[8:9], 0, v[240:241]
	v_lshl_add_u64 v[238:239], v[238:239], 0, v[152:153]
	v_lshl_add_u64 v[240:241], v[240:241], 0, v[152:153]
	global_load_dwordx4 v[200:203], v[238:239], off offset:2048 nt
	global_load_dwordx4 v[204:207], v[240:241], off
	global_load_dwordx4 v[208:211], v[240:241], off offset:256
	global_load_dwordx4 v[212:215], v[238:239], off offset:2304 nt
	s_nop 0
	v_add_u32_e32 v236, 0x10, v154
	v_ashrrev_i32_e32 v237, 31, v236
	v_lshlrev_b64 v[238:239], 12, v[236:237]
	v_lshlrev_b64 v[240:241], 11, v[236:237]
	v_lshl_add_u64 v[238:239], s[88:89], 0, v[238:239]
	v_lshl_add_u64 v[240:241], s[8:9], 0, v[240:241]
	v_lshl_add_u64 v[238:239], v[238:239], 0, v[152:153]
	v_lshl_add_u64 v[240:241], v[240:241], 0, v[152:153]
	global_load_dwordx4 v[216:219], v[238:239], off offset:2048 nt
	global_load_dwordx4 v[220:223], v[240:241], off
	global_load_dwordx4 v[228:231], v[240:241], off offset:256
	global_load_dwordx4 v[232:235], v[238:239], off offset:2304 nt
	s_nop 0
	v_lshl_add_u64 v[180:181], s[8:9], 0, v[184:185]
	v_lshl_add_u64 v[188:189], v[176:177], 0, v[152:153]
	v_lshl_add_u64 v[186:187], v[180:181], 0, v[152:153]
	v_lshl_add_u64 v[184:185], s[10:11], 0, v[184:185]
	v_lshl_add_u64 v[190:191], v[184:185], 0, v[152:153]
	s_andn2_b64 vcc, exec, s[6:7]
	s_mov_b64 s[6:7], -1
	s_waitcnt vmcnt(7)
	v_lshlrev_b32_e32 v192, 16, v200
	v_and_b32_e32 v193, 0xffff0000, v200
	s_waitcnt vmcnt(6)
	v_lshlrev_b32_e32 v194, 16, v204
	v_and_b32_e32 v195, 0xffff0000, v204
	v_lshlrev_b32_e32 v176, 16, v201
	v_and_b32_e32 v177, 0xffff0000, v201
	v_lshlrev_b32_e32 v180, 16, v205
	v_and_b32_e32 v181, 0xffff0000, v205
	v_lshlrev_b32_e32 v196, 16, v202
	v_and_b32_e32 v197, 0xffff0000, v202
	v_lshlrev_b32_e32 v198, 16, v206
	v_and_b32_e32 v199, 0xffff0000, v206
	v_lshlrev_b32_e32 v178, 16, v203
	v_and_b32_e32 v179, 0xffff0000, v203
	v_lshlrev_b32_e32 v182, 16, v207
	v_and_b32_e32 v183, 0xffff0000, v207
	v_pk_fma_f32 v[124:125], v[124:125], v[192:193], v[194:195]
	v_pk_fma_f32 v[126:127], v[126:127], v[176:177], v[180:181]
	v_pk_fma_f32 v[176:177], v[120:121], v[196:197], v[198:199]
	v_pk_fma_f32 v[178:179], v[122:123], v[178:179], v[182:183]
	v_cvt_pk_bf16_f32 v120, v124, v125
	v_cvt_pk_bf16_f32 v121, v126, v127
	v_cvt_pk_bf16_f32 v122, v176, v177
	v_cvt_pk_bf16_f32 v123, v178, v179
	global_store_dwordx4 v[190:191], v[120:123], off
	v_or_b32_e32 v124, 16, v154
	s_waitcnt vmcnt(6)
	v_lshlrev_b32_e32 v178, 16, v208
	v_and_b32_e32 v179, 0xffff0000, v208
	v_lshlrev_b32_e32 v180, 16, v209
	v_and_b32_e32 v181, 0xffff0000, v209
	v_lshlrev_b32_e32 v182, 16, v210
	v_and_b32_e32 v183, 0xffff0000, v210
	v_lshlrev_b32_e32 v184, 16, v211
	v_and_b32_e32 v185, 0xffff0000, v211
	v_ashrrev_i32_e32 v125, 31, v124
	v_lshlrev_b64 v[126:127], 12, v[124:125]
	v_lshlrev_b64 v[124:125], 11, v[124:125]
	v_lshl_add_u64 v[126:127], s[88:89], 0, v[126:127]
	v_lshl_add_u64 v[176:177], s[8:9], 0, v[124:125]
	v_lshl_add_u64 v[126:127], v[126:127], 0, v[152:153]
	s_waitcnt vmcnt(5)
	v_lshlrev_b32_e32 v186, 16, v212
	v_and_b32_e32 v187, 0xffff0000, v212
	v_lshlrev_b32_e32 v120, 16, v213
	v_and_b32_e32 v121, 0xffff0000, v213
	v_lshlrev_b32_e32 v188, 16, v214
	v_and_b32_e32 v189, 0xffff0000, v214
	v_lshlrev_b32_e32 v122, 16, v215
	v_and_b32_e32 v123, 0xffff0000, v215
	v_add_u32_e32 v236, 0x20, v154
	v_ashrrev_i32_e32 v237, 31, v236
	v_lshlrev_b64 v[238:239], 12, v[236:237]
	v_lshlrev_b64 v[240:241], 11, v[236:237]
	v_lshl_add_u64 v[238:239], s[88:89], 0, v[238:239]
	v_lshl_add_u64 v[240:241], s[8:9], 0, v[240:241]
	v_lshl_add_u64 v[238:239], v[238:239], 0, v[152:153]
	v_lshl_add_u64 v[240:241], v[240:241], 0, v[152:153]
	global_load_dwordx4 v[200:203], v[238:239], off offset:2048 nt
	global_load_dwordx4 v[204:207], v[240:241], off
	global_load_dwordx4 v[208:211], v[240:241], off offset:256
	global_load_dwordx4 v[212:215], v[238:239], off offset:2304 nt
	s_nop 0
	v_pk_fma_f32 v[116:117], v[116:117], v[186:187], v[178:179]
	v_pk_fma_f32 v[118:119], v[118:119], v[120:121], v[180:181]
	v_pk_fma_f32 v[120:121], v[112:113], v[188:189], v[182:183]
	v_pk_fma_f32 v[122:123], v[114:115], v[122:123], v[184:185]
	v_cvt_pk_bf16_f32 v112, v116, v117
	v_cvt_pk_bf16_f32 v113, v118, v119
	v_cvt_pk_bf16_f32 v114, v120, v121
	v_cvt_pk_bf16_f32 v115, v122, v123
	global_store_dwordx4 v[190:191], v[112:115], off offset:256
	v_lshl_add_u64 v[120:121], v[176:177], 0, v[152:153]
	v_lshl_add_u64 v[122:123], s[10:11], 0, v[124:125]
	v_lshl_add_u64 v[124:125], v[122:123], 0, v[152:153]
	s_waitcnt vmcnt(9)
	v_lshlrev_b32_e32 v176, 16, v216
	v_and_b32_e32 v177, 0xffff0000, v216
	s_waitcnt vmcnt(8)
; __device__ __forceinline__ unsigned pk_bf16(float lo, float hi) { const f32x2 v = {lo, hi}; return __builtin_bit_cast(unsigned, __builtin_convertvector(v, b16x2)); }
;     __device__ __forceinline__ void row(int r, int col32, int fq, const f32x4& a00, const f32x4& a01, const f32x4& a10, const f32x4& a11) const { half(r, col32, fq, a00, a01); half(r, col32 + HALF, fq, a10, a11); }
;     __device__ __forceinline__ void row(int r, int col32, int fq, const f32x4& a00, const f32x4& a01, const f32x4& a10, const f32x4& a11) const { half(r, col32, fq, a00, a01); half(r, col32 + HALF, fq, a10, a11); }
;     __device__ __forceinline__ void row(int r, int col32, int fq, const f32x4& a00, const f32x4& a01, const f32x4& a10, const f32x4& a11) const { half(r, col32, fq, a00, a01); half(r, col32 + HALF, fq, a10, a11); }
;     __device__ __forceinline__ void half(int row, int col32, int fq, const f32x4& v0, const f32x4& v1) const {
;         const int col = col32 + 8 * fq;
;         float g[8], a[8]; bf8_to_f(*(const u32x4*)(gates + (size_t)row * 2048 + 1024 + col), g); bf8_to_f(*(const u32x4*)(t1 + (size_t)row * D + col), a);
;         u32x4 w; w.x = pk_bf16(a[0] + v0[0] * g[0], a[1] + v0[1] * g[1]); w.y = pk_bf16(a[2] + v0[2] * g[2], a[3] + v0[3] * g[3]);
;         w.z = pk_bf16(a[4] + v1[0] * g[4], a[5] + v1[1] * g[5]); w.w = pk_bf16(a[6] + v1[2] * g[6], a[7] + v1[3] * g[7]);
;         *(u32x4*)(m + (size_t)row * D + col) = w;
;     }
	v_lshlrev_b32_e32 v178, 16, v220
	v_and_b32_e32 v179, 0xffff0000, v220
	v_lshlrev_b32_e32 v112, 16, v217
	v_and_b32_e32 v113, 0xffff0000, v217
	v_lshlrev_b32_e32 v116, 16, v221
	v_and_b32_e32 v117, 0xffff0000, v221
	v_lshlrev_b32_e32 v180, 16, v218
	v_and_b32_e32 v181, 0xffff0000, v218
	v_lshlrev_b32_e32 v182, 16, v222
	v_and_b32_e32 v183, 0xffff0000, v222
	v_lshlrev_b32_e32 v114, 16, v219
	v_and_b32_e32 v115, 0xffff0000, v219
	v_lshlrev_b32_e32 v118, 16, v223
	v_and_b32_e32 v119, 0xffff0000, v223
	v_pk_fma_f32 v[108:109], v[108:109], v[176:177], v[178:179]
	v_pk_fma_f32 v[110:111], v[110:111], v[112:113], v[116:117]
	v_pk_fma_f32 v[112:113], v[104:105], v[180:181], v[182:183]
	v_pk_fma_f32 v[114:115], v[106:107], v[114:115], v[118:119]
	v_cvt_pk_bf16_f32 v104, v108, v109
	v_cvt_pk_bf16_f32 v105, v110, v111
	v_cvt_pk_bf16_f32 v106, v112, v113
	v_cvt_pk_bf16_f32 v107, v114, v115
	global_store_dwordx4 v[124:125], v[104:107], off
	v_or_b32_e32 v108, 32, v154
	s_waitcnt vmcnt(8)
	v_lshlrev_b32_e32 v114, 16, v228
	v_and_b32_e32 v115, 0xffff0000, v228
	v_lshlrev_b32_e32 v116, 16, v229
	v_and_b32_e32 v117, 0xffff0000, v229
	v_lshlrev_b32_e32 v118, 16, v230
	v_and_b32_e32 v119, 0xffff0000, v230
	v_lshlrev_b32_e32 v120, 16, v231
	v_and_b32_e32 v121, 0xffff0000, v231
	v_ashrrev_i32_e32 v109, 31, v108
	v_lshlrev_b64 v[110:111], 12, v[108:109]
	v_lshlrev_b64 v[108:109], 11, v[108:109]
	v_lshl_add_u64 v[110:111], s[88:89], 0, v[110:111]
	v_lshl_add_u64 v[112:113], s[8:9], 0, v[108:109]
	v_lshl_add_u64 v[110:111], v[110:111], 0, v[152:153]
	s_waitcnt vmcnt(7)
	v_lshlrev_b32_e32 v122, 16, v232
	v_and_b32_e32 v123, 0xffff0000, v232
	v_lshlrev_b32_e32 v104, 16, v233
	v_and_b32_e32 v105, 0xffff0000, v233
	v_lshlrev_b32_e32 v126, 16, v234
	v_and_b32_e32 v127, 0xffff0000, v234
	v_lshlrev_b32_e32 v106, 16, v235
	v_and_b32_e32 v107, 0xffff0000, v235
	v_add_u32_e32 v236, 0x30, v154
	v_ashrrev_i32_e32 v237, 31, v236
	v_lshlrev_b64 v[238:239], 12, v[236:237]
	v_lshlrev_b64 v[240:241], 11, v[236:237]
	v_lshl_add_u64 v[238:239], s[88:89], 0, v[238:239]
	v_lshl_add_u64 v[240:241], s[8:9], 0, v[240:241]
	v_lshl_add_u64 v[238:239], v[238:239], 0, v[152:153]
	v_lshl_add_u64 v[240:241], v[240:241], 0, v[152:153]
	global_load_dwordx4 v[216:219], v[238:239], off offset:2048 nt
	global_load_dwordx4 v[220:223], v[240:241], off
	global_load_dwordx4 v[228:231], v[240:241], off offset:256
	global_load_dwordx4 v[232:235], v[238:239], off offset:2304 nt
	s_nop 0
	v_pk_fma_f32 v[100:101], v[100:101], v[122:123], v[114:115]
	v_pk_fma_f32 v[102:103], v[102:103], v[104:105], v[116:117]
	v_pk_fma_f32 v[104:105], v[96:97], v[126:127], v[118:119]
	v_pk_fma_f32 v[106:107], v[98:99], v[106:107], v[120:121]
	v_cvt_pk_bf16_f32 v96, v100, v101
	v_cvt_pk_bf16_f32 v97, v102, v103
	v_cvt_pk_bf16_f32 v98, v104, v105
	v_cvt_pk_bf16_f32 v99, v106, v107
	global_store_dwordx4 v[124:125], v[96:99], off offset:256
	v_lshl_add_u64 v[104:105], v[112:113], 0, v[152:153]
	v_lshl_add_u64 v[106:107], s[10:11], 0, v[108:109]
	v_lshl_add_u64 v[108:109], v[106:107], 0, v[152:153]
	s_waitcnt vmcnt(10)
	v_lshlrev_b32_e32 v112, 16, v200
	v_and_b32_e32 v113, 0xffff0000, v200
	s_waitcnt vmcnt(9)
	v_lshlrev_b32_e32 v114, 16, v204
	v_and_b32_e32 v115, 0xffff0000, v204
	v_lshlrev_b32_e32 v96, 16, v201
	v_and_b32_e32 v97, 0xffff0000, v201
	v_lshlrev_b32_e32 v100, 16, v205
	v_and_b32_e32 v101, 0xffff0000, v205
	v_lshlrev_b32_e32 v116, 16, v202
	v_and_b32_e32 v117, 0xffff0000, v202
	v_lshlrev_b32_e32 v118, 16, v206
	v_and_b32_e32 v119, 0xffff0000, v206
	v_lshlrev_b32_e32 v98, 16, v203
	v_and_b32_e32 v99, 0xffff0000, v203
	v_lshlrev_b32_e32 v102, 16, v207
	v_and_b32_e32 v103, 0xffff0000, v207
	v_pk_fma_f32 v[92:93], v[92:93], v[112:113], v[114:115]
	v_pk_fma_f32 v[94:95], v[94:95], v[96:97], v[100:101]
	v_pk_fma_f32 v[96:97], v[88:89], v[116:117], v[118:119]
	v_pk_fma_f32 v[98:99], v[90:91], v[98:99], v[102:103]
	v_cvt_pk_bf16_f32 v88, v92, v93
	v_cvt_pk_bf16_f32 v89, v94, v95
	v_cvt_pk_bf16_f32 v90, v96, v97
	v_cvt_pk_bf16_f32 v91, v98, v99
	global_store_dwordx4 v[108:109], v[88:91], off
	v_or_b32_e32 v92, 48, v154
	s_waitcnt vmcnt(9)
	v_lshlrev_b32_e32 v98, 16, v208
	v_and_b32_e32 v99, 0xffff0000, v208
	v_lshlrev_b32_e32 v100, 16, v209
	v_and_b32_e32 v101, 0xffff0000, v209
	v_lshlrev_b32_e32 v102, 16, v210
	v_and_b32_e32 v103, 0xffff0000, v210
	v_lshlrev_b32_e32 v104, 16, v211
	v_and_b32_e32 v105, 0xffff0000, v211
	v_ashrrev_i32_e32 v93, 31, v92
	v_lshlrev_b64 v[94:95], 12, v[92:93]
	v_lshlrev_b64 v[92:93], 11, v[92:93]
	v_lshl_add_u64 v[94:95], s[88:89], 0, v[94:95]
	v_lshl_add_u64 v[96:97], s[8:9], 0, v[92:93]
	v_lshl_add_u64 v[94:95], v[94:95], 0, v[152:153]
	s_waitcnt vmcnt(8)
	v_lshlrev_b32_e32 v106, 16, v212
	v_and_b32_e32 v107, 0xffff0000, v212
	v_lshlrev_b32_e32 v88, 16, v213
	v_and_b32_e32 v89, 0xffff0000, v213
	v_lshlrev_b32_e32 v110, 16, v214
	v_and_b32_e32 v111, 0xffff0000, v214
	v_lshlrev_b32_e32 v90, 16, v215
	v_and_b32_e32 v91, 0xffff0000, v215
	v_add_u32_e32 v236, 0x80, v154
	v_ashrrev_i32_e32 v237, 31, v236
	v_lshlrev_b64 v[238:239], 12, v[236:237]
	v_lshlrev_b64 v[240:241], 11, v[236:237]
	v_lshl_add_u64 v[238:239], s[88:89], 0, v[238:239]
	v_lshl_add_u64 v[240:241], s[8:9], 0, v[240:241]
	v_lshl_add_u64 v[238:239], v[238:239], 0, v[152:153]
	v_lshl_add_u64 v[240:241], v[240:241], 0, v[152:153]
	global_load_dwordx4 v[200:203], v[238:239], off offset:2048 nt
	global_load_dwordx4 v[204:207], v[240:241], off
	global_load_dwordx4 v[208:211], v[240:241], off offset:256
	global_load_dwordx4 v[212:215], v[238:239], off offset:2304 nt
	s_nop 0
	v_pk_fma_f32 v[84:85], v[84:85], v[106:107], v[98:99]
	v_pk_fma_f32 v[86:87], v[86:87], v[88:89], v[100:101]
	v_pk_fma_f32 v[88:89], v[80:81], v[110:111], v[102:103]
	v_pk_fma_f32 v[90:91], v[82:83], v[90:91], v[104:105]
	v_cvt_pk_bf16_f32 v80, v84, v85
	v_cvt_pk_bf16_f32 v81, v86, v87
	v_cvt_pk_bf16_f32 v82, v88, v89
	v_cvt_pk_bf16_f32 v83, v90, v91
	global_store_dwordx4 v[108:109], v[80:83], off offset:256
	v_lshl_add_u64 v[88:89], v[96:97], 0, v[152:153]
	v_lshl_add_u64 v[90:91], s[10:11], 0, v[92:93]
	v_lshl_add_u64 v[92:93], v[90:91], 0, v[152:153]
	s_waitcnt vmcnt(10)
; __device__ __forceinline__ unsigned pk_bf16(float lo, float hi) { const f32x2 v = {lo, hi}; return __builtin_bit_cast(unsigned, __builtin_convertvector(v, b16x2)); }
;     __device__ __forceinline__ void row(int r, int col32, int fq, const f32x4& a00, const f32x4& a01, const f32x4& a10, const f32x4& a11) const { half(r, col32, fq, a00, a01); half(r, col32 + HALF, fq, a10, a11); }
;     __device__ __forceinline__ void row(int r, int col32, int fq, const f32x4& a00, const f32x4& a01, const f32x4& a10, const f32x4& a11) const { half(r, col32, fq, a00, a01); half(r, col32 + HALF, fq, a10, a11); }
;     __device__ __forceinline__ void row(int r, int col32, int fq, const f32x4& a00, const f32x4& a01, const f32x4& a10, const f32x4& a11) const { half(r, col32, fq, a00, a01); half(r, col32 + HALF, fq, a10, a11); }
;     __device__ __forceinline__ void half(int row, int col32, int fq, const f32x4& v0, const f32x4& v1) const {
;         const int col = col32 + 8 * fq;
;         float g[8], a[8]; bf8_to_f(*(const u32x4*)(gates + (size_t)row * 2048 + 1024 + col), g); bf8_to_f(*(const u32x4*)(t1 + (size_t)row * D + col), a);
;         u32x4 w; w.x = pk_bf16(a[0] + v0[0] * g[0], a[1] + v0[1] * g[1]); w.y = pk_bf16(a[2] + v0[2] * g[2], a[3] + v0[3] * g[3]);
;         w.z = pk_bf16(a[4] + v1[0] * g[4], a[5] + v1[1] * g[5]); w.w = pk_bf16(a[6] + v1[2] * g[6], a[7] + v1[3] * g[7]);
;         *(u32x4*)(m + (size_t)row * D + col) = w;
;     }
	v_lshlrev_b32_e32 v96, 16, v216
	v_and_b32_e32 v97, 0xffff0000, v216
	s_waitcnt vmcnt(9)
	v_lshlrev_b32_e32 v98, 16, v220
	v_and_b32_e32 v99, 0xffff0000, v220
	v_lshlrev_b32_e32 v80, 16, v217
	v_and_b32_e32 v81, 0xffff0000, v217
	v_lshlrev_b32_e32 v84, 16, v221
	v_and_b32_e32 v85, 0xffff0000, v221
	v_lshlrev_b32_e32 v100, 16, v218
	v_and_b32_e32 v101, 0xffff0000, v218
	v_lshlrev_b32_e32 v102, 16, v222
	v_and_b32_e32 v103, 0xffff0000, v222
	v_lshlrev_b32_e32 v82, 16, v219
	v_and_b32_e32 v83, 0xffff0000, v219
	v_lshlrev_b32_e32 v86, 16, v223
	v_and_b32_e32 v87, 0xffff0000, v223
	v_pk_fma_f32 v[76:77], v[76:77], v[96:97], v[98:99]
	v_pk_fma_f32 v[78:79], v[78:79], v[80:81], v[84:85]
	v_pk_fma_f32 v[80:81], v[72:73], v[100:101], v[102:103]
	v_pk_fma_f32 v[82:83], v[74:75], v[82:83], v[86:87]
	v_cvt_pk_bf16_f32 v72, v76, v77
	v_cvt_pk_bf16_f32 v73, v78, v79
	v_cvt_pk_bf16_f32 v74, v80, v81
	v_cvt_pk_bf16_f32 v75, v82, v83
	global_store_dwordx4 v[92:93], v[72:75], off
	v_add_u32_e32 v76, 0x80, v154
	s_waitcnt vmcnt(9)
	v_lshlrev_b32_e32 v82, 16, v228
	v_and_b32_e32 v83, 0xffff0000, v228
	v_lshlrev_b32_e32 v84, 16, v229
	v_and_b32_e32 v85, 0xffff0000, v229
	v_lshlrev_b32_e32 v86, 16, v230
	v_and_b32_e32 v87, 0xffff0000, v230
	v_lshlrev_b32_e32 v88, 16, v231
	v_and_b32_e32 v89, 0xffff0000, v231
	v_ashrrev_i32_e32 v77, 31, v76
	v_lshlrev_b64 v[78:79], 12, v[76:77]
	v_lshlrev_b64 v[76:77], 11, v[76:77]
	v_lshl_add_u64 v[78:79], s[88:89], 0, v[78:79]
	v_lshl_add_u64 v[80:81], s[8:9], 0, v[76:77]
	v_lshl_add_u64 v[78:79], v[78:79], 0, v[152:153]
	s_waitcnt vmcnt(8)
	v_lshlrev_b32_e32 v90, 16, v232
	v_and_b32_e32 v91, 0xffff0000, v232
	v_lshlrev_b32_e32 v72, 16, v233
	v_and_b32_e32 v73, 0xffff0000, v233
	v_lshlrev_b32_e32 v94, 16, v234
	v_and_b32_e32 v95, 0xffff0000, v234
	v_lshlrev_b32_e32 v74, 16, v235
	v_and_b32_e32 v75, 0xffff0000, v235
	v_add_u32_e32 v236, 0x90, v154
	v_ashrrev_i32_e32 v237, 31, v236
	v_lshlrev_b64 v[238:239], 12, v[236:237]
	v_lshlrev_b64 v[240:241], 11, v[236:237]
	v_lshl_add_u64 v[238:239], s[88:89], 0, v[238:239]
	v_lshl_add_u64 v[240:241], s[8:9], 0, v[240:241]
	v_lshl_add_u64 v[238:239], v[238:239], 0, v[152:153]
	v_lshl_add_u64 v[240:241], v[240:241], 0, v[152:153]
	global_load_dwordx4 v[216:219], v[238:239], off offset:2048 nt
	global_load_dwordx4 v[220:223], v[240:241], off
	global_load_dwordx4 v[228:231], v[240:241], off offset:256
	global_load_dwordx4 v[232:235], v[238:239], off offset:2304 nt
	s_nop 0
	v_pk_fma_f32 v[68:69], v[68:69], v[90:91], v[82:83]
	v_pk_fma_f32 v[70:71], v[70:71], v[72:73], v[84:85]
	v_pk_fma_f32 v[72:73], v[64:65], v[94:95], v[86:87]
	v_pk_fma_f32 v[74:75], v[66:67], v[74:75], v[88:89]
	v_cvt_pk_bf16_f32 v64, v68, v69
	v_cvt_pk_bf16_f32 v65, v70, v71
	v_cvt_pk_bf16_f32 v66, v72, v73
	v_cvt_pk_bf16_f32 v67, v74, v75
	global_store_dwordx4 v[92:93], v[64:67], off offset:256
	v_lshl_add_u64 v[72:73], v[80:81], 0, v[152:153]
	v_lshl_add_u64 v[74:75], s[10:11], 0, v[76:77]
	v_lshl_add_u64 v[76:77], v[74:75], 0, v[152:153]
	s_waitcnt vmcnt(10)
	v_lshlrev_b32_e32 v80, 16, v200
	v_and_b32_e32 v81, 0xffff0000, v200
	s_waitcnt vmcnt(9)
	v_lshlrev_b32_e32 v82, 16, v204
	v_and_b32_e32 v83, 0xffff0000, v204
	v_lshlrev_b32_e32 v64, 16, v201
	v_and_b32_e32 v65, 0xffff0000, v201
	v_lshlrev_b32_e32 v68, 16, v205
	v_and_b32_e32 v69, 0xffff0000, v205
	v_lshlrev_b32_e32 v84, 16, v202
	v_and_b32_e32 v85, 0xffff0000, v202
	v_lshlrev_b32_e32 v86, 16, v206
	v_and_b32_e32 v87, 0xffff0000, v206
	v_lshlrev_b32_e32 v66, 16, v203
	v_and_b32_e32 v67, 0xffff0000, v203
	v_lshlrev_b32_e32 v70, 16, v207
	v_and_b32_e32 v71, 0xffff0000, v207
	v_pk_fma_f32 v[60:61], v[60:61], v[80:81], v[82:83]
	v_pk_fma_f32 v[62:63], v[62:63], v[64:65], v[68:69]
	v_pk_fma_f32 v[64:65], v[56:57], v[84:85], v[86:87]
	v_pk_fma_f32 v[66:67], v[58:59], v[66:67], v[70:71]
	v_cvt_pk_bf16_f32 v56, v60, v61
	v_cvt_pk_bf16_f32 v57, v62, v63
	v_cvt_pk_bf16_f32 v58, v64, v65
	v_cvt_pk_bf16_f32 v59, v66, v67
	global_store_dwordx4 v[76:77], v[56:59], off
	v_add_u32_e32 v60, 0x90, v154
	s_waitcnt vmcnt(9)
	v_lshlrev_b32_e32 v66, 16, v208
	v_and_b32_e32 v67, 0xffff0000, v208
	v_lshlrev_b32_e32 v68, 16, v209
	v_and_b32_e32 v69, 0xffff0000, v209
	v_lshlrev_b32_e32 v70, 16, v210
	v_and_b32_e32 v71, 0xffff0000, v210
	v_lshlrev_b32_e32 v72, 16, v211
	v_and_b32_e32 v73, 0xffff0000, v211
	v_ashrrev_i32_e32 v61, 31, v60
	v_lshlrev_b64 v[62:63], 12, v[60:61]
	v_lshlrev_b64 v[60:61], 11, v[60:61]
	v_lshl_add_u64 v[62:63], s[88:89], 0, v[62:63]
	v_lshl_add_u64 v[64:65], s[8:9], 0, v[60:61]
	v_lshl_add_u64 v[62:63], v[62:63], 0, v[152:153]
	s_waitcnt vmcnt(8)
	v_lshlrev_b32_e32 v74, 16, v212
	v_and_b32_e32 v75, 0xffff0000, v212
	v_lshlrev_b32_e32 v56, 16, v213
	v_and_b32_e32 v57, 0xffff0000, v213
	v_lshlrev_b32_e32 v78, 16, v214
	v_and_b32_e32 v79, 0xffff0000, v214
	v_lshlrev_b32_e32 v58, 16, v215
	v_and_b32_e32 v59, 0xffff0000, v215
	v_add_u32_e32 v236, 0xa0, v154
	v_ashrrev_i32_e32 v237, 31, v236
	v_lshlrev_b64 v[238:239], 12, v[236:237]
	v_lshlrev_b64 v[240:241], 11, v[236:237]
	v_lshl_add_u64 v[238:239], s[88:89], 0, v[238:239]
	v_lshl_add_u64 v[240:241], s[8:9], 0, v[240:241]
	v_lshl_add_u64 v[238:239], v[238:239], 0, v[152:153]
	v_lshl_add_u64 v[240:241], v[240:241], 0, v[152:153]
	global_load_dwordx4 v[200:203], v[238:239], off offset:2048 nt
	global_load_dwordx4 v[204:207], v[240:241], off
	global_load_dwordx4 v[208:211], v[240:241], off offset:256
	global_load_dwordx4 v[212:215], v[238:239], off offset:2304 nt
	s_nop 0
	v_pk_fma_f32 v[52:53], v[52:53], v[74:75], v[66:67]
	v_pk_fma_f32 v[54:55], v[54:55], v[56:57], v[68:69]
	v_pk_fma_f32 v[56:57], v[48:49], v[78:79], v[70:71]
	v_pk_fma_f32 v[58:59], v[50:51], v[58:59], v[72:73]
	v_cvt_pk_bf16_f32 v48, v52, v53
	v_cvt_pk_bf16_f32 v49, v54, v55
	v_cvt_pk_bf16_f32 v50, v56, v57
	v_cvt_pk_bf16_f32 v51, v58, v59
	global_store_dwordx4 v[76:77], v[48:51], off offset:256
	v_lshl_add_u64 v[56:57], v[64:65], 0, v[152:153]
	v_lshl_add_u64 v[58:59], s[10:11], 0, v[60:61]
	v_lshl_add_u64 v[60:61], v[58:59], 0, v[152:153]
	s_waitcnt vmcnt(10)
; __device__ __forceinline__ unsigned pk_bf16(float lo, float hi) { const f32x2 v = {lo, hi}; return __builtin_bit_cast(unsigned, __builtin_convertvector(v, b16x2)); }
;     __device__ __forceinline__ void row(int r, int col32, int fq, const f32x4& a00, const f32x4& a01, const f32x4& a10, const f32x4& a11) const { half(r, col32, fq, a00, a01); half(r, col32 + HALF, fq, a10, a11); }
;     __device__ __forceinline__ void row(int r, int col32, int fq, const f32x4& a00, const f32x4& a01, const f32x4& a10, const f32x4& a11) const { half(r, col32, fq, a00, a01); half(r, col32 + HALF, fq, a10, a11); }
;     __device__ __forceinline__ void row(int r, int col32, int fq, const f32x4& a00, const f32x4& a01, const f32x4& a10, const f32x4& a11) const { half(r, col32, fq, a00, a01); half(r, col32 + HALF, fq, a10, a11); }
;     __device__ __forceinline__ void half(int row, int col32, int fq, const f32x4& v0, const f32x4& v1) const {
;         const int col = col32 + 8 * fq;
;         float g[8], a[8]; bf8_to_f(*(const u32x4*)(gates + (size_t)row * 2048 + 1024 + col), g); bf8_to_f(*(const u32x4*)(t1 + (size_t)row * D + col), a);
;         u32x4 w; w.x = pk_bf16(a[0] + v0[0] * g[0], a[1] + v0[1] * g[1]); w.y = pk_bf16(a[2] + v0[2] * g[2], a[3] + v0[3] * g[3]);
;         w.z = pk_bf16(a[4] + v1[0] * g[4], a[5] + v1[1] * g[5]); w.w = pk_bf16(a[6] + v1[2] * g[6], a[7] + v1[3] * g[7]);
;         *(u32x4*)(m + (size_t)row * D + col) = w;
;     }
	v_lshlrev_b32_e32 v64, 16, v216
	v_and_b32_e32 v65, 0xffff0000, v216
	s_waitcnt vmcnt(9)
	v_lshlrev_b32_e32 v66, 16, v220
	v_and_b32_e32 v67, 0xffff0000, v220
	v_lshlrev_b32_e32 v48, 16, v217
	v_and_b32_e32 v49, 0xffff0000, v217
	v_lshlrev_b32_e32 v52, 16, v221
	v_and_b32_e32 v53, 0xffff0000, v221
	v_lshlrev_b32_e32 v68, 16, v218
	v_and_b32_e32 v69, 0xffff0000, v218
	v_lshlrev_b32_e32 v70, 16, v222
	v_and_b32_e32 v71, 0xffff0000, v222
	v_lshlrev_b32_e32 v50, 16, v219
	v_and_b32_e32 v51, 0xffff0000, v219
	v_lshlrev_b32_e32 v54, 16, v223
	v_and_b32_e32 v55, 0xffff0000, v223
	v_pk_fma_f32 v[44:45], v[44:45], v[64:65], v[66:67]
	v_pk_fma_f32 v[46:47], v[46:47], v[48:49], v[52:53]
	v_pk_fma_f32 v[48:49], v[40:41], v[68:69], v[70:71]
	v_pk_fma_f32 v[50:51], v[42:43], v[50:51], v[54:55]
	v_cvt_pk_bf16_f32 v40, v44, v45
	v_cvt_pk_bf16_f32 v41, v46, v47
	v_cvt_pk_bf16_f32 v42, v48, v49
	v_cvt_pk_bf16_f32 v43, v50, v51
	global_store_dwordx4 v[60:61], v[40:43], off
	v_add_u32_e32 v44, 0xa0, v154
	s_waitcnt vmcnt(9)
	v_lshlrev_b32_e32 v50, 16, v228
	v_and_b32_e32 v51, 0xffff0000, v228
	v_lshlrev_b32_e32 v52, 16, v229
	v_and_b32_e32 v53, 0xffff0000, v229
	v_lshlrev_b32_e32 v54, 16, v230
	v_and_b32_e32 v55, 0xffff0000, v230
	v_lshlrev_b32_e32 v56, 16, v231
	v_and_b32_e32 v57, 0xffff0000, v231
	v_ashrrev_i32_e32 v45, 31, v44
	v_lshlrev_b64 v[46:47], 12, v[44:45]
	v_lshlrev_b64 v[44:45], 11, v[44:45]
	v_lshl_add_u64 v[46:47], s[88:89], 0, v[46:47]
	v_lshl_add_u64 v[48:49], s[8:9], 0, v[44:45]
	v_lshl_add_u64 v[46:47], v[46:47], 0, v[152:153]
	s_waitcnt vmcnt(8)
	v_lshlrev_b32_e32 v58, 16, v232
	v_and_b32_e32 v59, 0xffff0000, v232
	v_lshlrev_b32_e32 v40, 16, v233
	v_and_b32_e32 v41, 0xffff0000, v233
	v_lshlrev_b32_e32 v62, 16, v234
	v_and_b32_e32 v63, 0xffff0000, v234
	v_lshlrev_b32_e32 v42, 16, v235
	v_and_b32_e32 v43, 0xffff0000, v235
	v_add_u32_e32 v236, 0xb0, v154
	v_ashrrev_i32_e32 v237, 31, v236
	v_lshlrev_b64 v[238:239], 12, v[236:237]
	v_lshlrev_b64 v[240:241], 11, v[236:237]
	v_lshl_add_u64 v[238:239], s[88:89], 0, v[238:239]
	v_lshl_add_u64 v[240:241], s[8:9], 0, v[240:241]
	v_lshl_add_u64 v[238:239], v[238:239], 0, v[152:153]
	v_lshl_add_u64 v[240:241], v[240:241], 0, v[152:153]
	global_load_dwordx4 v[216:219], v[238:239], off offset:2048 nt
	global_load_dwordx4 v[220:223], v[240:241], off
	global_load_dwordx4 v[228:231], v[240:241], off offset:256
	global_load_dwordx4 v[232:235], v[238:239], off offset:2304 nt
	s_nop 0
	v_pk_fma_f32 v[36:37], v[36:37], v[58:59], v[50:51]
	v_pk_fma_f32 v[38:39], v[38:39], v[40:41], v[52:53]
	v_pk_fma_f32 v[40:41], v[32:33], v[62:63], v[54:55]
	v_pk_fma_f32 v[42:43], v[34:35], v[42:43], v[56:57]
	v_cvt_pk_bf16_f32 v32, v36, v37
	v_cvt_pk_bf16_f32 v33, v38, v39
	v_cvt_pk_bf16_f32 v34, v40, v41
	v_cvt_pk_bf16_f32 v35, v42, v43
	global_store_dwordx4 v[60:61], v[32:35], off offset:256
	v_lshl_add_u64 v[40:41], v[48:49], 0, v[152:153]
	v_lshl_add_u64 v[42:43], s[10:11], 0, v[44:45]
	v_lshl_add_u64 v[44:45], v[42:43], 0, v[152:153]
	s_waitcnt vmcnt(10)
	v_lshlrev_b32_e32 v48, 16, v200
	v_and_b32_e32 v49, 0xffff0000, v200
	s_waitcnt vmcnt(9)
	v_lshlrev_b32_e32 v50, 16, v204
	v_and_b32_e32 v51, 0xffff0000, v204
	v_lshlrev_b32_e32 v32, 16, v201
	v_and_b32_e32 v33, 0xffff0000, v201
	v_lshlrev_b32_e32 v36, 16, v205
	v_and_b32_e32 v37, 0xffff0000, v205
	v_lshlrev_b32_e32 v52, 16, v202
	v_and_b32_e32 v53, 0xffff0000, v202
	v_lshlrev_b32_e32 v54, 16, v206
	v_and_b32_e32 v55, 0xffff0000, v206
	v_lshlrev_b32_e32 v34, 16, v203
	v_and_b32_e32 v35, 0xffff0000, v203
	v_lshlrev_b32_e32 v38, 16, v207
	v_and_b32_e32 v39, 0xffff0000, v207
	v_pk_fma_f32 v[28:29], v[28:29], v[48:49], v[50:51]
	v_pk_fma_f32 v[30:31], v[30:31], v[32:33], v[36:37]
	v_pk_fma_f32 v[32:33], v[24:25], v[52:53], v[54:55]
	v_pk_fma_f32 v[34:35], v[26:27], v[34:35], v[38:39]
	v_cvt_pk_bf16_f32 v24, v28, v29
	v_cvt_pk_bf16_f32 v25, v30, v31
	v_cvt_pk_bf16_f32 v26, v32, v33
	v_cvt_pk_bf16_f32 v27, v34, v35
	global_store_dwordx4 v[44:45], v[24:27], off
	v_add_u32_e32 v28, 0xb0, v154
	s_waitcnt vmcnt(9)
; __device__ __forceinline__ unsigned pk_bf16(float lo, float hi) { const f32x2 v = {lo, hi}; return __builtin_bit_cast(unsigned, __builtin_convertvector(v, b16x2)); }
; #define PG8_BAR __builtin_amdgcn_s_barrier()
;     __device__ __forceinline__ void row(int r, int col32, int fq, const f32x4& a00, const f32x4& a01, const f32x4& a10, const f32x4& a11) const { half(r, col32, fq, a00, a01); half(r, col32 + HALF, fq, a10, a11); }
;     __device__ __forceinline__ void row(int r, int col32, int fq, const f32x4& a00, const f32x4& a01, const f32x4& a10, const f32x4& a11) const { half(r, col32, fq, a00, a01); half(r, col32 + HALF, fq, a10, a11); }
;     ...
;         if (!has_next) break;
; #pragma unroll
;         for (int a = 0; a < 2; ++a)
; #pragma unroll
;             for (int b = 0; b < 2; ++b)
; #pragma unroll
;                 for (int m = 0; m < 4; ++m)
; #pragma unroll
;                     for (int n = 0; n < 2; ++n) acc[a][b][m][n] = (f32x4){0.f, 0.f, 0.f, 0.f};
;         cur = nxt; cA = nA; cB = nB; ++ui;
;         if (wr == 1) PG8_BAR;
;     __device__ __forceinline__ void half(int row, int col32, int fq, const f32x4& v0, const f32x4& v1) const {
;         const int col = col32 + 8 * fq;
;         float g[8], a[8]; bf8_to_f(*(const u32x4*)(gates + (size_t)row * 2048 + 1024 + col), g); bf8_to_f(*(const u32x4*)(t1 + (size_t)row * D + col), a);
;         u32x4 w; w.x = pk_bf16(a[0] + v0[0] * g[0], a[1] + v0[1] * g[1]); w.y = pk_bf16(a[2] + v0[2] * g[2], a[3] + v0[3] * g[3]);
;         w.z = pk_bf16(a[4] + v1[0] * g[4], a[5] + v1[1] * g[5]); w.w = pk_bf16(a[6] + v1[2] * g[6], a[7] + v1[3] * g[7]);
;         *(u32x4*)(m + (size_t)row * D + col) = w;
;     }
;     __device__ __forceinline__ void row(int r, int col32, int fq, const f32x4& a00, const f32x4& a01, const f32x4& a10, const f32x4& a11) const { half(r, col32, fq, a00, a01); half(r, col32 + HALF, fq, a10, a11); }
	v_lshlrev_b32_e32 v34, 16, v208
	v_and_b32_e32 v35, 0xffff0000, v208
	v_lshlrev_b32_e32 v36, 16, v209
	v_and_b32_e32 v37, 0xffff0000, v209
	v_lshlrev_b32_e32 v38, 16, v210
	v_and_b32_e32 v39, 0xffff0000, v210
	v_lshlrev_b32_e32 v40, 16, v211
	v_and_b32_e32 v41, 0xffff0000, v211
	v_ashrrev_i32_e32 v29, 31, v28
	v_lshlrev_b64 v[30:31], 12, v[28:29]
	v_lshlrev_b64 v[28:29], 11, v[28:29]
	v_lshl_add_u64 v[30:31], s[88:89], 0, v[30:31]
	v_lshl_add_u64 v[32:33], s[8:9], 0, v[28:29]
	v_lshl_add_u64 v[30:31], v[30:31], 0, v[152:153]
	s_waitcnt vmcnt(8)
	v_lshlrev_b32_e32 v42, 16, v212
	v_and_b32_e32 v43, 0xffff0000, v212
	v_lshlrev_b32_e32 v24, 16, v213
	v_and_b32_e32 v25, 0xffff0000, v213
	v_lshlrev_b32_e32 v46, 16, v214
	v_and_b32_e32 v47, 0xffff0000, v214
	v_lshlrev_b32_e32 v26, 16, v215
	v_and_b32_e32 v27, 0xffff0000, v215
	v_pk_fma_f32 v[20:21], v[20:21], v[42:43], v[34:35]
	v_pk_fma_f32 v[22:23], v[22:23], v[24:25], v[36:37]
	v_pk_fma_f32 v[24:25], v[16:17], v[46:47], v[38:39]
	v_pk_fma_f32 v[26:27], v[18:19], v[26:27], v[40:41]
	v_cvt_pk_bf16_f32 v16, v20, v21
	v_cvt_pk_bf16_f32 v17, v22, v23
	v_cvt_pk_bf16_f32 v18, v24, v25
	v_cvt_pk_bf16_f32 v19, v26, v27
	global_store_dwordx4 v[44:45], v[16:19], off offset:256
	v_lshl_add_u64 v[24:25], v[32:33], 0, v[152:153]
	v_lshl_add_u64 v[26:27], s[10:11], 0, v[28:29]
	v_lshl_add_u64 v[28:29], v[26:27], 0, v[152:153]
	s_waitcnt vmcnt(6)
	v_lshlrev_b32_e32 v32, 16, v216
	v_and_b32_e32 v33, 0xffff0000, v216
	s_waitcnt vmcnt(5)
	v_lshlrev_b32_e32 v34, 16, v220
	v_and_b32_e32 v35, 0xffff0000, v220
	v_lshlrev_b32_e32 v16, 16, v217
	v_and_b32_e32 v17, 0xffff0000, v217
	v_lshlrev_b32_e32 v20, 16, v221
	v_and_b32_e32 v21, 0xffff0000, v221
	v_lshlrev_b32_e32 v36, 16, v218
	v_and_b32_e32 v37, 0xffff0000, v218
	v_lshlrev_b32_e32 v38, 16, v222
	v_and_b32_e32 v39, 0xffff0000, v222
	v_lshlrev_b32_e32 v18, 16, v219
	v_and_b32_e32 v19, 0xffff0000, v219
	v_lshlrev_b32_e32 v22, 16, v223
	v_and_b32_e32 v23, 0xffff0000, v223
	v_pk_fma_f32 v[12:13], v[12:13], v[32:33], v[34:35]
	v_pk_fma_f32 v[14:15], v[14:15], v[16:17], v[20:21]
	v_pk_fma_f32 v[16:17], v[8:9], v[36:37], v[38:39]
	v_pk_fma_f32 v[18:19], v[10:11], v[18:19], v[22:23]
	v_cvt_pk_bf16_f32 v8, v12, v13
	v_cvt_pk_bf16_f32 v9, v14, v15
	v_cvt_pk_bf16_f32 v10, v16, v17
	v_cvt_pk_bf16_f32 v11, v18, v19
	global_store_dwordx4 v[28:29], v[8:11], off
	s_waitcnt vmcnt(5)
	v_lshlrev_b32_e32 v12, 16, v228
	v_and_b32_e32 v13, 0xffff0000, v228
	v_lshlrev_b32_e32 v14, 16, v229
	v_and_b32_e32 v15, 0xffff0000, v229
	v_lshlrev_b32_e32 v16, 16, v230
	v_and_b32_e32 v17, 0xffff0000, v230
	v_lshlrev_b32_e32 v18, 16, v231
	v_and_b32_e32 v19, 0xffff0000, v231
	s_waitcnt vmcnt(4)
	v_lshlrev_b32_e32 v20, 16, v232
	v_and_b32_e32 v21, 0xffff0000, v232
	v_lshlrev_b32_e32 v8, 16, v233
	v_and_b32_e32 v9, 0xffff0000, v233
	v_lshlrev_b32_e32 v22, 16, v234
	v_and_b32_e32 v23, 0xffff0000, v234
	v_lshlrev_b32_e32 v10, 16, v235
	v_and_b32_e32 v11, 0xffff0000, v235
	v_pk_fma_f32 v[4:5], v[4:5], v[20:21], v[12:13]
	v_pk_fma_f32 v[6:7], v[6:7], v[8:9], v[14:15]
	v_pk_fma_f32 v[8:9], v[0:1], v[22:23], v[16:17]
	v_pk_fma_f32 v[10:11], v[2:3], v[10:11], v[18:19]
	v_cvt_pk_bf16_f32 v0, v4, v5
	v_cvt_pk_bf16_f32 v1, v6, v7
	v_cvt_pk_bf16_f32 v2, v8, v9
	v_cvt_pk_bf16_f32 v3, v10, v11
	global_store_dwordx4 v[28:29], v[0:3], off offset:256
	s_cbranch_vccnz .LBB0_1039
	s_andn2_b64 vcc, exec, s[0:1]
	s_cbranch_vccnz .LBB0_1038
	s_barrier
	s_branch .LBB0_1038

;     __device__ __forceinline__ void fused(f32x4 (&acc)[2][2][4][2], const Unit& u, int wr, int wc, int fr, int fq, int wid, int lane) const {
;     ...
;         u32x4 hres[2][4][2];
; #pragma unroll
;         for (int ai = 0; ai < 2; ++ai)
; #pragma unroll
;             for (int m = 0; m < 4; ++m) {
;                 const bf16_t* q = h1b + (size_t)(u.pm * BM + ai * HALF + wr * 64 + m * 16 + fr) * D + col0;
; #pragma unroll
;                 for (int bj = 0; bj < 2; ++bj) hres[ai][m][bj] = *(const u32x4*)(q + bj * HALF);
;             }
; #pragma unroll
;         for (int ai = 0; ai < 2; ++ai)
; #pragma unroll
;             for (int m = 0; m < 4; ++m) {
;                 float sq = 0.f;
; #pragma unroll
;                 for (int bj = 0; bj < 2; ++bj)
; #pragma unroll
;                     for (int n = 0; n < 2; ++n) { const f32x4 x = acc[ai][bj][m][n]; sq += (x[0] * x[0] + x[1] * x[1]) + (x[2] * x[2] + x[3] * x[3]); }
;                 sq += __shfl_xor(sq, 16); sq += __shfl_xor(sq, 32);
;                 if (fq == 0) Pl[(ai * HALF + wr * 64 + m * 16 + fr) * 4 + wc] = sq;
;             }
.LBB0_1331:
	s_lshl_b32 s30, s48, 8
	v_lshl_or_b32 v176, s26, 8, v247
	v_add_u32_e32 v222, s30, v228
	v_ashrrev_i32_e32 v177, 31, v176
	v_ashrrev_i32_e32 v223, 31, v222
	v_lshl_add_u64 v[104:105], v[176:177], 1, s[10:11]
	v_lshlrev_b64 v[106:107], 11, v[222:223]
	v_lshl_add_u64 v[106:107], v[104:105], 0, v[106:107]
	global_load_dwordx4 v[204:207], v[106:107], off nt
	global_load_dwordx4 v[200:203], v[106:107], off offset:256 nt
	v_or_b32_e32 v106, 16, v222
	v_ashrrev_i32_e32 v107, 31, v106
	v_lshlrev_b64 v[106:107], 11, v[106:107]
	v_lshl_add_u64 v[106:107], v[104:105], 0, v[106:107]
	global_load_dwordx4 v[196:199], v[106:107], off nt
	global_load_dwordx4 v[192:195], v[106:107], off offset:256 nt
	v_or_b32_e32 v106, 32, v222
	v_ashrrev_i32_e32 v107, 31, v106
	v_lshlrev_b64 v[106:107], 11, v[106:107]
	v_lshl_add_u64 v[106:107], v[104:105], 0, v[106:107]
	global_load_dwordx4 v[172:175], v[106:107], off nt
	global_load_dwordx4 v[168:171], v[106:107], off offset:256 nt
	v_or_b32_e32 v106, 48, v222
	v_ashrrev_i32_e32 v107, 31, v106
	v_lshlrev_b64 v[106:107], 11, v[106:107]
	v_lshl_add_u64 v[106:107], v[104:105], 0, v[106:107]
	global_load_dwordx4 v[164:167], v[106:107], off nt
	global_load_dwordx4 v[160:163], v[106:107], off offset:256 nt
	v_add_u32_e32 v106, 0x80, v222
	v_ashrrev_i32_e32 v107, 31, v106
	v_lshlrev_b64 v[106:107], 11, v[106:107]
	v_lshl_add_u64 v[106:107], v[104:105], 0, v[106:107]
	global_load_dwordx4 v[152:155], v[106:107], off nt
	global_load_dwordx4 v[144:147], v[106:107], off offset:256 nt
	v_add_u32_e32 v106, 0x90, v222
	v_ashrrev_i32_e32 v107, 31, v106
	v_lshlrev_b64 v[106:107], 11, v[106:107]
	v_lshl_add_u64 v[106:107], v[104:105], 0, v[106:107]
	global_load_dwordx4 v[140:143], v[106:107], off nt
	global_load_dwordx4 v[132:135], v[106:107], off offset:256 nt
	v_add_u32_e32 v106, 0xa0, v222
	v_ashrrev_i32_e32 v107, 31, v106
	v_lshlrev_b64 v[106:107], 11, v[106:107]
	v_lshl_add_u64 v[106:107], v[104:105], 0, v[106:107]
	global_load_dwordx4 v[124:127], v[106:107], off nt
	global_load_dwordx4 v[116:119], v[106:107], off offset:256 nt
	v_add_u32_e32 v106, 0xb0, v222
	v_ashrrev_i32_e32 v107, 31, v106
	v_lshlrev_b64 v[106:107], 11, v[106:107]
	v_lshl_add_u64 v[104:105], v[104:105], 0, v[106:107]
	global_load_dwordx4 v[108:111], v[104:105], off nt
	s_nop 0
	global_load_dwordx4 v[104:107], v[104:105], off offset:256 nt
	v_mul_f32_e32 v179, v157, v157
	v_mul_f32_e32 v180, v159, v159
	v_fmac_f32_e32 v179, v156, v156
	v_fmac_f32_e32 v180, v158, v158
	v_add_f32_e32 v179, v179, v180
	v_mul_f32_e32 v180, v149, v149
	v_mul_f32_e32 v181, v151, v151
	v_fmac_f32_e32 v180, v148, v148
	v_fmac_f32_e32 v181, v150, v150
	v_add_f32_e32 v180, v180, v181
	v_add_f32_e32 v179, v179, v180
	v_mul_f32_e32 v180, v137, v137
	v_mul_f32_e32 v181, v139, v139
	v_fmac_f32_e32 v180, v136, v136
	v_fmac_f32_e32 v181, v138, v138
	v_add_f32_e32 v180, v180, v181
	v_mov_b32_e32 v178, v253
	v_add_f32_e32 v179, v179, v180
	v_mul_f32_e32 v180, v129, v129
	v_mul_f32_e32 v181, v131, v131
	v_cmp_lt_i32_e32 vcc, v178, v227
	v_fmac_f32_e32 v180, v128, v128
	v_fmac_f32_e32 v181, v130, v130
	v_cndmask_b32_e32 v178, v254, v178, vcc
	v_add_f32_e32 v180, v180, v181
	v_lshlrev_b32_e32 v178, 2, v178
	v_add_f32_e32 v180, v179, v180
	ds_bpermute_b32 v181, v178, v180
	v_xor_b32_e32 v179, 32, v254
	v_cmp_lt_i32_e32 vcc, v179, v227
	s_waitcnt lgkmcnt(0)
	v_add_f32_e32 v180, v180, v181
	v_cndmask_b32_e32 v179, v254, v179, vcc
	v_lshlrev_b32_e32 v179, 2, v179
	ds_bpermute_b32 v181, v179, v180
	s_and_saveexec_b64 s[28:29], s[0:1]
	s_cbranch_execz .LBB0_1333
	s_waitcnt lgkmcnt(0)
	v_add_f32_e32 v180, v180, v181
	ds_write_b32 v252, v180
